# attention loop: V-fragment prefetch + wave halves staggered by one PV block (split barrier position) + s_setprio 1 in QK/exp blocks, 0 in PV blocks
# speedup vs baseline: 1.0271x; 1.0075x over previous
.LBB0_597:
	s_setprio 0
	s_and_b64 vcc, exec, s[98:99]
	v_cvt_pk_bf16_f32 v96, v112, v113
	v_cvt_pk_bf16_f32 v97, v116, v115
	v_cvt_pk_bf16_f32 v98, v118, v119
	v_cvt_pk_bf16_f32 v99, v120, v117
	v_cvt_pk_bf16_f32 v100, v114, v121
	v_cvt_pk_bf16_f32 v101, v122, v123
	v_cvt_pk_bf16_f32 v102, v124, v125
	v_cvt_pk_bf16_f32 v103, v126, v127
	ds_read_b64_tr_b16 v[104:105], v244 offset:61440
	ds_read_b64_tr_b16 v[106:107], v244 offset:63488
	ds_read_b64_tr_b16 v[108:109], v245 offset:61440
	ds_read_b64_tr_b16 v[110:111], v245 offset:63488
	ds_read_b64_tr_b16 v[112:113], v246 offset:61440
	ds_read_b64_tr_b16 v[114:115], v246 offset:63488
	ds_read_b64_tr_b16 v[116:117], v247 offset:61440
	ds_read_b64_tr_b16 v[118:119], v247 offset:63488
	s_add_i32 s65, s65, 1
	s_add_u32 s36, s36, 0x10000
	s_addc_u32 s37, s37, 0
	s_addk_i32 s69, 0x4000
	s_add_i32 s70, s70, 64
	s_add_u32 s38, s38, 0x10000
	s_addc_u32 s39, s39, 0
	s_add_i32 s71, s71, 1
	s_add_i32 s46, s46, 1
	v_add_f32_e32 v162, v163, v162
	s_cmp_eq_u32 s69, 0x100000
	s_cbranch_vccz .Lat_skip_p1
	s_waitcnt vmcnt(0) lgkmcnt(0)
	s_barrier
.Lat_skip_p1:
	v_mfma_f32_32x32x16_bf16 v[48:63], v[228:231], v[96:99], v[48:63]
	v_mfma_f32_32x32x16_bf16 v[32:47], v[232:235], v[96:99], v[32:47]
	v_mfma_f32_32x32x16_bf16 v[16:31], v[236:239], v[96:99], v[16:31]
	v_mfma_f32_32x32x16_bf16 v[0:15], v[240:243], v[96:99], v[0:15]
	s_waitcnt lgkmcnt(6)
	v_mfma_f32_32x32x16_bf16 v[48:63], v[104:107], v[100:103], v[48:63]
	s_waitcnt lgkmcnt(4)
	v_mfma_f32_32x32x16_bf16 v[32:47], v[108:111], v[100:103], v[32:47]
	s_waitcnt lgkmcnt(2)
	v_mfma_f32_32x32x16_bf16 v[16:31], v[112:115], v[100:103], v[16:31]
	s_waitcnt lgkmcnt(0)
	v_mfma_f32_32x32x16_bf16 v[0:15], v[116:119], v[100:103], v[0:15]
	s_cbranch_vccnz .Lat_skip_p0
	s_waitcnt vmcnt(0) lgkmcnt(0)
	s_barrier

.LBB0_605:
	s_setprio 1
	s_add_i32 s0, s69, 0xffffc000
	s_and_b32 s0, s0, 0x4000
	v_add_u32_e32 v244, s0, v176
	v_add_u32_e32 v245, s0, v177
	v_add_u32_e32 v246, s0, v178
	v_add_u32_e32 v247, s0, v179
	ds_read_b64_tr_b16 v[228:229], v244 offset:49152
	ds_read_b64_tr_b16 v[230:231], v244 offset:51200
	ds_read_b64_tr_b16 v[232:233], v245 offset:49152
	ds_read_b64_tr_b16 v[234:235], v245 offset:51200
	ds_read_b64_tr_b16 v[236:237], v246 offset:49152
	ds_read_b64_tr_b16 v[238:239], v246 offset:51200
	ds_read_b64_tr_b16 v[240:241], v247 offset:49152
	ds_read_b64_tr_b16 v[242:243], v247 offset:51200
	s_mul_hi_u32 s0, s46, 0xaaaaaaab
	s_lshr_b32 s0, s0, 1
	s_mul_i32 s0, s0, 0xffff4000
	v_add_u32_e32 v96, s0, v193
	v_add_u32_e32 v163, s69, v173
	v_add3_u32 v96, v96, v163, s57
	ds_read_b128 v[114:117], v96
	v_add_u32_e32 v122, s0, v191
	v_add3_u32 v122, v122, v163, s57
	ds_read_b128 v[122:125], v122
	v_add_u32_e32 v96, s0, v192
	v_add3_u32 v96, v96, v163, s57
	v_add_u32_e32 v126, s0, v190
	ds_read_b128 v[118:121], v96
	v_add3_u32 v126, v126, v163, s57
	ds_read_b128 v[206:209], v126
	s_waitcnt lgkmcnt(3)
	v_mfma_f32_32x32x16_bf16 v[96:111], v[114:117], v[140:143], v[64:79]
	v_exp_f32_e32 v112, v80
	v_exp_f32_e32 v113, v81
	v_exp_f32_e32 v114, v82
	v_exp_f32_e32 v115, v83
	v_exp_f32_e32 v116, v84
	v_exp_f32_e32 v117, v85
	s_waitcnt lgkmcnt(1)
	v_mfma_f32_32x32x16_bf16 v[96:111], v[118:121], v[136:139], v[96:111]
	v_exp_f32_e32 v118, v86
	v_exp_f32_e32 v119, v87
	v_exp_f32_e32 v120, v88
	v_exp_f32_e32 v121, v89
	v_mfma_f32_32x32x16_bf16 v[96:111], v[122:125], v[132:135], v[96:111]
	v_add_f32_e32 v123, 0, v112
	v_add_f32_e32 v123, v113, v123
	v_add_f32_e32 v123, v114, v123
	v_add_f32_e32 v123, v115, v123
	v_add_f32_e32 v123, v116, v123
	v_add_f32_e32 v123, v117, v123
	v_exp_f32_e32 v122, v90
	v_add_f32_e32 v123, v118, v123
	v_add_f32_e32 v123, v119, v123
	v_add_f32_e32 v123, v120, v123
	v_add_f32_e32 v123, v121, v123
	v_add_f32_e32 v124, v122, v123
	v_exp_f32_e32 v123, v91
	s_waitcnt lgkmcnt(0)
	v_mfma_f32_32x32x16_bf16 v[96:111], v[206:209], v[128:131], v[96:111]
	v_add_f32_e32 v125, v123, v124
	v_exp_f32_e32 v124, v92
	s_nop 0
	v_add_f32_e32 v126, v124, v125
	v_exp_f32_e32 v125, v93
	s_nop 0
	v_add_f32_e32 v127, v125, v126
	v_exp_f32_e32 v126, v94
	s_nop 0
	v_add_f32_e32 v164, v126, v127
	v_exp_f32_e32 v127, v95
	s_nop 0
	v_add_f32_e32 v209, v127, v164
	v_cmp_nge_f32_e32 vcc, s56, v209
	s_cbranch_vccz .LBB0_607
	v_max_f32_e32 v112, v81, v81
	v_max_f32_e32 v113, v80, v80
	v_max_f32_e32 v112, v113, v112
	v_max3_f32 v112, v112, v82, v83
	v_max3_f32 v112, v112, v84, v85
	v_max3_f32 v112, v112, v86, v87
	v_max3_f32 v112, v112, v88, v89
	v_max3_f32 v112, v112, v90, v91
	v_max3_f32 v112, v112, v92, v93
	v_max3_f32 v112, v112, v94, v95
	v_mov_b32_e32 v113, v112
	s_nop 1
	v_permlane32_swap_b32_e32 v112, v113
	v_max3_f32 v121, v112, v113, 0
	v_sub_f32_e32 v80, v80, v121
	v_exp_f32_e32 v112, v80
	v_sub_f32_e32 v81, v81, v121
	v_exp_f32_e32 v113, v81
	v_sub_f32_e32 v81, v82, v121
	v_exp_f32_e32 v114, v81
	v_sub_f32_e32 v81, v83, v121
	v_exp_f32_e32 v115, v81
	v_sub_f32_e32 v81, v84, v121
	v_add_f32_e32 v117, 0, v112
	v_exp_f32_e32 v116, v81
	v_sub_f32_e32 v82, v85, v121
	v_add_f32_e32 v81, v113, v117
	v_exp_f32_e32 v117, v82
	v_sub_f32_e32 v82, v86, v121
	v_add_f32_e32 v81, v114, v81
	v_exp_f32_e32 v118, v82
	v_sub_f32_e32 v82, v87, v121
	v_add_f32_e32 v81, v115, v81
	v_exp_f32_e32 v119, v82
	v_sub_f32_e32 v82, v88, v121
	v_add_f32_e32 v81, v116, v81
	v_sub_f32_e32 v83, v89, v121
	v_exp_f32_e32 v120, v82
	v_exp_f32_e64 v80, -v121
	v_sub_f32_e32 v84, v90, v121
	v_sub_f32_e32 v85, v91, v121
	v_sub_f32_e32 v86, v92, v121
	v_sub_f32_e32 v87, v93, v121
	v_sub_f32_e32 v88, v94, v121
	v_sub_f32_e32 v89, v95, v121
	v_add_f32_e32 v81, v117, v81
	v_sub_f32_e32 v111, v111, v121
	v_sub_f32_e32 v110, v110, v121
	v_sub_f32_e32 v109, v109, v121
	v_sub_f32_e32 v108, v108, v121
	v_sub_f32_e32 v107, v107, v121
	v_sub_f32_e32 v106, v106, v121
	v_sub_f32_e32 v105, v105, v121
	v_sub_f32_e32 v104, v104, v121
	v_sub_f32_e32 v103, v103, v121
	v_sub_f32_e32 v102, v102, v121
	v_sub_f32_e32 v101, v101, v121
	v_sub_f32_e32 v100, v100, v121
	v_sub_f32_e32 v99, v99, v121
	v_sub_f32_e32 v98, v98, v121
	v_sub_f32_e32 v97, v97, v121
	v_sub_f32_e32 v96, v96, v121
	v_sub_f32_e32 v79, v79, v121
	v_sub_f32_e32 v78, v78, v121
	v_sub_f32_e32 v77, v77, v121
	v_sub_f32_e32 v76, v76, v121
	v_sub_f32_e32 v75, v75, v121
	v_sub_f32_e32 v74, v74, v121
	v_sub_f32_e32 v73, v73, v121
	v_sub_f32_e32 v72, v72, v121
	v_sub_f32_e32 v71, v71, v121
	v_sub_f32_e32 v70, v70, v121
	v_sub_f32_e32 v69, v69, v121
	v_sub_f32_e32 v68, v68, v121
	v_sub_f32_e32 v67, v67, v121
	v_sub_f32_e32 v66, v66, v121
	v_sub_f32_e32 v65, v65, v121
	v_sub_f32_e32 v64, v64, v121
	v_exp_f32_e32 v121, v83
	v_add_f32_e32 v81, v118, v81
	v_exp_f32_e32 v122, v84
	v_add_f32_e32 v81, v119, v81
	v_exp_f32_e32 v123, v85
	v_add_f32_e32 v81, v120, v81
	v_exp_f32_e32 v124, v86
	v_pk_mul_f32 v[62:63], v[62:63], v[80:81] op_sel_hi:[1,0]
	v_pk_mul_f32 v[60:61], v[60:61], v[80:81] op_sel_hi:[1,0]
	v_pk_mul_f32 v[58:59], v[58:59], v[80:81] op_sel_hi:[1,0]
	v_pk_mul_f32 v[56:57], v[56:57], v[80:81] op_sel_hi:[1,0]
	v_pk_mul_f32 v[54:55], v[54:55], v[80:81] op_sel_hi:[1,0]
	v_pk_mul_f32 v[52:53], v[52:53], v[80:81] op_sel_hi:[1,0]
	v_pk_mul_f32 v[50:51], v[50:51], v[80:81] op_sel_hi:[1,0]
	v_pk_mul_f32 v[48:49], v[48:49], v[80:81] op_sel_hi:[1,0]
	v_pk_mul_f32 v[46:47], v[46:47], v[80:81] op_sel_hi:[1,0]
	v_pk_mul_f32 v[44:45], v[44:45], v[80:81] op_sel_hi:[1,0]
	v_pk_mul_f32 v[42:43], v[42:43], v[80:81] op_sel_hi:[1,0]
	v_pk_mul_f32 v[40:41], v[40:41], v[80:81] op_sel_hi:[1,0]
	v_pk_mul_f32 v[38:39], v[38:39], v[80:81] op_sel_hi:[1,0]
	v_pk_mul_f32 v[36:37], v[36:37], v[80:81] op_sel_hi:[1,0]
	v_pk_mul_f32 v[34:35], v[34:35], v[80:81] op_sel_hi:[1,0]
	v_pk_mul_f32 v[32:33], v[32:33], v[80:81] op_sel_hi:[1,0]
	v_pk_mul_f32 v[30:31], v[30:31], v[80:81] op_sel_hi:[1,0]
	v_pk_mul_f32 v[28:29], v[28:29], v[80:81] op_sel_hi:[1,0]
	v_pk_mul_f32 v[26:27], v[26:27], v[80:81] op_sel_hi:[1,0]
	v_pk_mul_f32 v[24:25], v[24:25], v[80:81] op_sel_hi:[1,0]
	v_pk_mul_f32 v[22:23], v[22:23], v[80:81] op_sel_hi:[1,0]
	v_pk_mul_f32 v[20:21], v[20:21], v[80:81] op_sel_hi:[1,0]
	v_pk_mul_f32 v[18:19], v[18:19], v[80:81] op_sel_hi:[1,0]
	v_pk_mul_f32 v[16:17], v[16:17], v[80:81] op_sel_hi:[1,0]
	v_pk_mul_f32 v[14:15], v[14:15], v[80:81] op_sel_hi:[1,0]
	v_pk_mul_f32 v[12:13], v[12:13], v[80:81] op_sel_hi:[1,0]
	v_pk_mul_f32 v[10:11], v[10:11], v[80:81] op_sel_hi:[1,0]
	v_pk_mul_f32 v[8:9], v[8:9], v[80:81] op_sel_hi:[1,0]
	v_pk_mul_f32 v[6:7], v[6:7], v[80:81] op_sel_hi:[1,0]
	v_pk_mul_f32 v[4:5], v[4:5], v[80:81] op_sel_hi:[1,0]
	v_pk_mul_f32 v[2:3], v[2:3], v[80:81] op_sel_hi:[1,0]
	v_pk_mul_f32 v[0:1], v[0:1], v[80:81] op_sel_hi:[1,0]
	v_mul_f32_e32 v162, v162, v80
	v_add_f32_e32 v80, v121, v81
	v_exp_f32_e32 v125, v87
	v_add_f32_e32 v80, v122, v80
	v_exp_f32_e32 v126, v88
	v_add_f32_e32 v80, v123, v80
	v_exp_f32_e32 v127, v89
	v_add_f32_e32 v80, v124, v80
	v_add_f32_e32 v80, v125, v80
	v_add_f32_e32 v80, v126, v80
	v_add_f32_e32 v209, v127, v80
.LBB0_607:
	s_setprio 0
	v_cvt_pk_bf16_f32 v80, v112, v113
	v_cvt_pk_bf16_f32 v81, v114, v115
	v_cvt_pk_bf16_f32 v82, v116, v117
	v_cvt_pk_bf16_f32 v83, v118, v119
	ds_read_b64_tr_b16 v[88:89], v244 offset:53248
	ds_read_b64_tr_b16 v[90:91], v244 offset:55296
	ds_read_b64_tr_b16 v[92:93], v245 offset:53248
	ds_read_b64_tr_b16 v[94:95], v245 offset:55296
	v_cvt_pk_bf16_f32 v84, v120, v121
	v_cvt_pk_bf16_f32 v85, v122, v123
	v_cvt_pk_bf16_f32 v86, v124, v125
	v_cvt_pk_bf16_f32 v87, v126, v127
	ds_read_b64_tr_b16 v[112:113], v246 offset:53248
	ds_read_b64_tr_b16 v[114:115], v246 offset:55296
	ds_read_b64_tr_b16 v[116:117], v247 offset:53248
	ds_read_b64_tr_b16 v[118:119], v247 offset:55296
	v_mfma_f32_32x32x16_bf16 v[48:63], v[228:231], v[80:83], v[48:63]
	s_cmp_gt_u32 s70, s66
	s_cselect_b64 s[0:1], -1, 0
	s_and_b64 s[8:9], s[0:1], exec
	s_cselect_b32 s61, 2, 1
	v_mfma_f32_32x32x16_bf16 v[32:47], v[232:235], v[80:83], v[32:47]
	s_cmp_gt_i32 s70, s68
	s_cselect_b64 vcc, -1, 0
	s_and_b64 s[8:9], vcc, exec
	s_cselect_b32 s61, s61, 0
	v_mfma_f32_32x32x16_bf16 v[16:31], v[236:239], v[80:83], v[16:31]
	s_cmp_eq_u32 s61, s60
	v_mfma_f32_32x32x16_bf16 v[0:15], v[240:243], v[80:83], v[0:15]
	s_waitcnt lgkmcnt(6)
	v_mfma_f32_32x32x16_bf16 v[48:63], v[88:91], v[84:87], v[48:63]
	s_waitcnt lgkmcnt(4)
	v_mfma_f32_32x32x16_bf16 v[32:47], v[92:95], v[84:87], v[32:47]
	s_waitcnt lgkmcnt(2)
	v_mfma_f32_32x32x16_bf16 v[16:31], v[112:115], v[84:87], v[16:31]
	s_waitcnt lgkmcnt(0)
	v_mfma_f32_32x32x16_bf16 v[0:15], v[116:119], v[84:87], v[0:15]
	s_cbranch_scc1 .LBB0_609
	s_and_b64 s[8:9], vcc, s[0:1]
	v_cndmask_b32_e64 v80, 0, v161, s[8:9]
	s_cmp_eq_u32 s60, 0
	v_cndmask_b32_e32 v80, v160, v80, vcc
	s_cselect_b64 vcc, -1, 0
	s_cmp_eq_u32 s60, 2
	s_cselect_b64 s[8:9], -1, 0
	v_cndmask_b32_e64 v81, 0, v161, s[8:9]
	v_cndmask_b32_e32 v81, v81, v160, vcc
	v_sub_f32_e32 v80, v80, v81
	v_pk_add_f32 v[78:79], v[80:81], v[78:79] op_sel_hi:[0,1]
	v_pk_add_f32 v[76:77], v[80:81], v[76:77] op_sel_hi:[0,1]
	v_pk_add_f32 v[74:75], v[80:81], v[74:75] op_sel_hi:[0,1]
	v_pk_add_f32 v[72:73], v[80:81], v[72:73] op_sel_hi:[0,1]
	v_pk_add_f32 v[70:71], v[80:81], v[70:71] op_sel_hi:[0,1]
	v_pk_add_f32 v[68:69], v[80:81], v[68:69] op_sel_hi:[0,1]
	v_pk_add_f32 v[66:67], v[80:81], v[66:67] op_sel_hi:[0,1]
	v_pk_add_f32 v[64:65], v[80:81], v[64:65] op_sel_hi:[0,1]
	s_branch .LBB0_610

.LBB0_612:
	s_setprio 1
	ds_read_b64_tr_b16 v[228:229], v244 offset:57344
	ds_read_b64_tr_b16 v[230:231], v244 offset:59392
	ds_read_b64_tr_b16 v[232:233], v245 offset:57344
	ds_read_b64_tr_b16 v[234:235], v245 offset:59392
	ds_read_b64_tr_b16 v[236:237], v246 offset:57344
	ds_read_b64_tr_b16 v[238:239], v246 offset:59392
	ds_read_b64_tr_b16 v[240:241], v247 offset:57344
	ds_read_b64_tr_b16 v[242:243], v247 offset:59392
	s_mul_hi_u32 s0, s71, 0xaaaaaaab
	s_lshr_b32 s0, s0, 1
	s_mul_i32 s0, s0, 0xffff4000
	v_add3_u32 v80, v193, s0, v163
	ds_read_b128 v[112:115], v80
	v_add3_u32 v80, v192, s0, v163
	ds_read_b128 v[120:123], v80
	v_exp_f32_e32 v116, v98
	v_exp_f32_e32 v118, v100
	v_exp_f32_e32 v119, v101
	v_exp_f32_e32 v117, v103
	v_add_f32_e32 v162, v209, v162
	s_waitcnt lgkmcnt(1)
	v_mfma_f32_32x32x16_bf16 v[80:95], v[112:115], v[140:143], v[64:79]
	v_exp_f32_e32 v112, v96
	v_exp_f32_e32 v113, v97
	v_exp_f32_e32 v115, v99
	v_add3_u32 v114, v191, s0, v163
	ds_read_b128 v[124:127], v114
	s_waitcnt lgkmcnt(1)
	v_mfma_f32_32x32x16_bf16 v[80:95], v[120:123], v[136:139], v[80:95]
	v_add_f32_e32 v123, 0, v112
	v_add_f32_e32 v123, v113, v123
	v_exp_f32_e32 v120, v102
	v_add_f32_e32 v123, v116, v123
	v_add3_u32 v122, v190, s0, v163
	v_add_f32_e32 v123, v115, v123
	ds_read_b128 v[210:213], v122
	v_exp_f32_e32 v114, v104
	v_add_f32_e32 v123, v118, v123
	v_exp_f32_e32 v121, v105
	v_add_f32_e32 v123, v119, v123
	v_exp_f32_e32 v122, v106
	v_add_f32_e32 v123, v120, v123
	v_add_f32_e32 v123, v117, v123
	v_add_f32_e32 v123, v114, v123
	v_add_f32_e32 v123, v121, v123
	s_waitcnt lgkmcnt(1)
	v_mfma_f32_32x32x16_bf16 v[80:95], v[124:127], v[132:135], v[80:95]
	v_add_f32_e32 v124, v122, v123
	v_exp_f32_e32 v123, v107
	s_nop 0
	v_add_f32_e32 v125, v123, v124
	v_exp_f32_e32 v124, v108
	s_waitcnt lgkmcnt(0)
	v_mfma_f32_32x32x16_bf16 v[80:95], v[210:213], v[128:131], v[80:95]
	v_add_f32_e32 v126, v124, v125
	v_exp_f32_e32 v125, v109
	s_nop 0
	v_add_f32_e32 v127, v125, v126
	v_exp_f32_e32 v126, v110
	s_nop 0
	v_add_f32_e32 v163, v126, v127
	v_exp_f32_e32 v127, v111
	s_nop 0
	v_add_f32_e32 v163, v127, v163
	v_cmp_nge_f32_e32 vcc, s56, v163
	s_cbranch_vccz .LBB0_597
	v_max_f32_e32 v112, v97, v97
	v_max_f32_e32 v113, v96, v96
	v_max_f32_e32 v112, v113, v112
	v_max3_f32 v112, v112, v98, v99
	v_max3_f32 v112, v112, v100, v101
	v_max3_f32 v112, v112, v102, v103
	v_max3_f32 v112, v112, v104, v105
	v_max3_f32 v112, v112, v106, v107
	v_max3_f32 v112, v112, v108, v109
	v_max3_f32 v112, v112, v110, v111
	v_mov_b32_e32 v113, v112
	s_nop 1
	v_permlane32_swap_b32_e32 v112, v113
	v_max3_f32 v121, v112, v113, 0
	v_sub_f32_e32 v96, v96, v121
	v_exp_f32_e32 v112, v96
	v_sub_f32_e32 v97, v97, v121
	v_exp_f32_e32 v113, v97
	v_sub_f32_e32 v97, v98, v121
	v_exp_f32_e32 v116, v97
	v_sub_f32_e32 v97, v99, v121
	v_exp_f32_e32 v115, v97
	v_sub_f32_e32 v97, v100, v121
	v_add_f32_e32 v114, 0, v112
	v_exp_f32_e32 v118, v97
	v_sub_f32_e32 v98, v101, v121
	v_add_f32_e32 v97, v113, v114
	v_exp_f32_e32 v119, v98
	v_sub_f32_e32 v98, v102, v121
	v_add_f32_e32 v97, v116, v97
	v_exp_f32_e32 v120, v98
	v_sub_f32_e32 v98, v103, v121
	v_add_f32_e32 v97, v115, v97
	v_exp_f32_e32 v117, v98
	v_sub_f32_e32 v98, v104, v121
	v_add_f32_e32 v97, v118, v97
	v_sub_f32_e32 v99, v105, v121
	v_exp_f32_e32 v114, v98
	v_exp_f32_e64 v96, -v121
	v_sub_f32_e32 v100, v106, v121
	v_sub_f32_e32 v101, v107, v121
	v_sub_f32_e32 v102, v108, v121
	v_sub_f32_e32 v103, v109, v121
	v_sub_f32_e32 v104, v110, v121
	v_sub_f32_e32 v105, v111, v121
	v_add_f32_e32 v97, v119, v97
	v_sub_f32_e32 v95, v95, v121
	v_sub_f32_e32 v94, v94, v121
	v_sub_f32_e32 v93, v93, v121
	v_sub_f32_e32 v92, v92, v121
	v_sub_f32_e32 v91, v91, v121
	v_sub_f32_e32 v90, v90, v121
	v_sub_f32_e32 v89, v89, v121
	v_sub_f32_e32 v88, v88, v121
	v_sub_f32_e32 v87, v87, v121
	v_sub_f32_e32 v86, v86, v121
	v_sub_f32_e32 v85, v85, v121
	v_sub_f32_e32 v84, v84, v121
	v_sub_f32_e32 v83, v83, v121
	v_sub_f32_e32 v82, v82, v121
	v_sub_f32_e32 v81, v81, v121
	v_sub_f32_e32 v80, v80, v121
	v_sub_f32_e32 v79, v79, v121
	v_sub_f32_e32 v78, v78, v121
	v_sub_f32_e32 v77, v77, v121
	v_sub_f32_e32 v76, v76, v121
	v_sub_f32_e32 v75, v75, v121
	v_sub_f32_e32 v74, v74, v121
	v_sub_f32_e32 v73, v73, v121
	v_sub_f32_e32 v72, v72, v121
	v_sub_f32_e32 v71, v71, v121
	v_sub_f32_e32 v70, v70, v121
	v_sub_f32_e32 v69, v69, v121
	v_sub_f32_e32 v68, v68, v121
	v_sub_f32_e32 v67, v67, v121
	v_sub_f32_e32 v66, v66, v121
	v_sub_f32_e32 v65, v65, v121
	v_sub_f32_e32 v64, v64, v121
	v_exp_f32_e32 v121, v99
	v_add_f32_e32 v97, v120, v97
	v_exp_f32_e32 v122, v100
	v_add_f32_e32 v97, v117, v97
	v_exp_f32_e32 v123, v101
	v_add_f32_e32 v97, v114, v97
	v_exp_f32_e32 v124, v102
	v_pk_mul_f32 v[62:63], v[62:63], v[96:97] op_sel_hi:[1,0]
	v_pk_mul_f32 v[60:61], v[60:61], v[96:97] op_sel_hi:[1,0]
	v_pk_mul_f32 v[58:59], v[58:59], v[96:97] op_sel_hi:[1,0]
	v_pk_mul_f32 v[56:57], v[56:57], v[96:97] op_sel_hi:[1,0]
	v_pk_mul_f32 v[54:55], v[54:55], v[96:97] op_sel_hi:[1,0]
	v_pk_mul_f32 v[52:53], v[52:53], v[96:97] op_sel_hi:[1,0]
	v_pk_mul_f32 v[50:51], v[50:51], v[96:97] op_sel_hi:[1,0]
	v_pk_mul_f32 v[48:49], v[48:49], v[96:97] op_sel_hi:[1,0]
	v_pk_mul_f32 v[46:47], v[46:47], v[96:97] op_sel_hi:[1,0]
	v_pk_mul_f32 v[44:45], v[44:45], v[96:97] op_sel_hi:[1,0]
	v_pk_mul_f32 v[42:43], v[42:43], v[96:97] op_sel_hi:[1,0]
	v_pk_mul_f32 v[40:41], v[40:41], v[96:97] op_sel_hi:[1,0]
	v_pk_mul_f32 v[38:39], v[38:39], v[96:97] op_sel_hi:[1,0]
	v_pk_mul_f32 v[36:37], v[36:37], v[96:97] op_sel_hi:[1,0]
	v_pk_mul_f32 v[34:35], v[34:35], v[96:97] op_sel_hi:[1,0]
	v_pk_mul_f32 v[32:33], v[32:33], v[96:97] op_sel_hi:[1,0]
	v_pk_mul_f32 v[30:31], v[30:31], v[96:97] op_sel_hi:[1,0]
	v_pk_mul_f32 v[28:29], v[28:29], v[96:97] op_sel_hi:[1,0]
	v_pk_mul_f32 v[26:27], v[26:27], v[96:97] op_sel_hi:[1,0]
	v_pk_mul_f32 v[24:25], v[24:25], v[96:97] op_sel_hi:[1,0]
	v_pk_mul_f32 v[22:23], v[22:23], v[96:97] op_sel_hi:[1,0]
	v_pk_mul_f32 v[20:21], v[20:21], v[96:97] op_sel_hi:[1,0]
	v_pk_mul_f32 v[18:19], v[18:19], v[96:97] op_sel_hi:[1,0]
	v_pk_mul_f32 v[16:17], v[16:17], v[96:97] op_sel_hi:[1,0]
	v_pk_mul_f32 v[14:15], v[14:15], v[96:97] op_sel_hi:[1,0]
	v_pk_mul_f32 v[12:13], v[12:13], v[96:97] op_sel_hi:[1,0]
	v_pk_mul_f32 v[10:11], v[10:11], v[96:97] op_sel_hi:[1,0]
	v_pk_mul_f32 v[8:9], v[8:9], v[96:97] op_sel_hi:[1,0]
	v_pk_mul_f32 v[6:7], v[6:7], v[96:97] op_sel_hi:[1,0]
	v_pk_mul_f32 v[4:5], v[4:5], v[96:97] op_sel_hi:[1,0]
	v_pk_mul_f32 v[2:3], v[2:3], v[96:97] op_sel_hi:[1,0]
	v_pk_mul_f32 v[0:1], v[0:1], v[96:97] op_sel_hi:[1,0]
	v_mul_f32_e32 v162, v162, v96
	v_add_f32_e32 v96, v121, v97
	v_exp_f32_e32 v125, v103
	v_add_f32_e32 v96, v122, v96
	v_exp_f32_e32 v126, v104
	v_add_f32_e32 v96, v123, v96
	v_exp_f32_e32 v127, v105
	v_add_f32_e32 v96, v124, v96
	v_add_f32_e32 v96, v125, v96
	v_add_f32_e32 v96, v126, v96
	v_add_f32_e32 v163, v127, v96
	s_branch .LBB0_597
.LBB0_614:
	s_setprio 0
	s_cmp_eq_u32 s54, s61
	s_cbranch_scc1 .LBB0_616
	s_cmp_eq_u32 s61, 0
	s_cselect_b64 vcc, -1, 0
	s_cmp_eq_u32 s61, 2
	s_cselect_b64 s[6:7], -1, 0
	v_cndmask_b32_e64 v97, 0, v161, s[6:7]
	v_cndmask_b32_e64 v96, 0, v161, s[4:5]
	v_cndmask_b32_e32 v97, v97, v160, vcc
	v_sub_f32_e32 v96, v96, v97
	v_pk_add_f32 v[78:79], v[78:79], v[96:97] op_sel_hi:[1,0]
	v_pk_add_f32 v[76:77], v[76:77], v[96:97] op_sel_hi:[1,0]
	v_pk_add_f32 v[74:75], v[74:75], v[96:97] op_sel_hi:[1,0]
	v_pk_add_f32 v[72:73], v[72:73], v[96:97] op_sel_hi:[1,0]
	v_pk_add_f32 v[70:71], v[70:71], v[96:97] op_sel_hi:[1,0]
	v_pk_add_f32 v[68:69], v[68:69], v[96:97] op_sel_hi:[1,0]
	v_pk_add_f32 v[66:67], v[66:67], v[96:97] op_sel_hi:[1,0]
	v_pk_add_f32 v[64:65], v[64:65], v[96:97] op_sel_hi:[1,0]
